# P3 scan hand-written with remap: the 64 P4-GEMM workgroups take no scan work (their chunks go to waves 4-7 of workgroups 64-127), so with the split-phase barrier 4 their GEMM starts at barrier 3's rel
# speedup vs baseline: 1.0235x; 1.0048x over previous
; DI unsigned pk(float a, float b) { f32x2 v = {a, b}; bf16x2_t r = __builtin_convertvector(v, bf16x2_t); return __builtin_bit_cast(unsigned, r); }
; DI float bflo(unsigned u) { return __uint_as_float(u << 16); }
; DI float bfhi(unsigned u) { return __uint_as_float(u & 0xffff0000u); }
; DI float log2_gamma(int h) { return log2f(1.0f - exp2f(-5.0f - (float)h)); }
; DI void ret_scan(const Params& P, int G, int bx, int tid) {
;     const bf16_t* US = (const bf16_t*)(P.ws + WS_US); bf16_t* SB = (bf16_t*)(P.ws + WS_SB);
;     for (int idx = bx * 512 + tid; idx < NB * 4 * 4096; idx += G * 512) {
;         const int bh = idx >> 12, e4 = (idx & 4095) * 4, b = bh >> 2, h = bh & 3;
;         const float g64 = exp2f(64.0f * log2_gamma(h));
;         f32x4 s = {0.f, 0.f, 0.f, 0.f};
; #pragma unroll 8
;         for (int c = 0; c < 32; ++c) {
;             const size_t o = ((size_t)(b * 32 + c) * 4 + h) * 16384 + e4;
;             const u32x2 ub = __builtin_nontemporal_load((const u32x2*)(US + o));
;             s = s * g64 + (f32x4){bflo(ub.x), bfhi(ub.x), bflo(ub.y), bfhi(ub.y)};
;             u32x2 w = {pk(s[0], s[1]), pk(s[2], s[3])};
;             *(u32x2*)(SB + o) = w;
;         }
.LBB0_670:
	s_or_b64 exec, exec, s[0:1]
	s_waitcnt lgkmcnt(0)
	v_mov_b32_e32 v0, v175
	s_barrier
	v_readlane_b32 s0, v255, 13
	s_mov_b32 s98, s2
	v_mov_b32_e32 v48, v175
	s_cmp_lg_u32 s100, 0
	s_cbranch_scc1 .Lscan_plain
	s_cmpk_lt_u32 s2, 64
	s_cbranch_scc1 .Lscan_done
	s_cmp_lt_u32 s0, 4
	s_cbranch_scc1 .Lscan_go
	s_sub_u32 s98, s2, 64
	s_cmpk_lt_u32 s98, 64
	s_cbranch_scc0 .Lscan_done
	v_subrev_u32_e32 v48, 0x100, v175
	s_branch .Lscan_go
.Lscan_plain:
	s_cmp_gt_u32 s0, 3
	s_cbranch_scc1 .Lscan_done
.Lscan_go:
	s_bfe_u32 s1, s98, 0x20003
	v_cvt_f32_ubyte0_e32 v0, s1
	v_sub_f32_e32 v0, 0xc0a00000, v0
	v_exp_f32_e32 v0, v0
	s_nop 0
	v_sub_f32_e32 v0, 1.0, v0
	v_log_f32_e32 v0, v0
	s_nop 0
	v_mul_f32_e32 v0, 0x42800000, v0
	v_exp_f32_e32 v24, v0
	s_lshr_b32 s8, s98, 5
	s_lshl_b32 s8, s8, 22
	s_lshl_b32 s9, s1, 15
	s_add_u32 s8, s8, s9
	s_add_u32 s42, s8, 0x9a00000
	s_add_u32 s34, s68, s42
	s_addc_u32 s35, s69, 0
	s_add_u32 s42, s8, 0xda00000
	s_add_u32 s36, s68, s42
	s_addc_u32 s37, s69, 0
	s_lshr_b32 s9, s98, 3
	s_lshl_b32 s9, s9, 16
	s_add_u32 s42, s9, 0x4500000
	s_add_u32 s38, s62, s42
	s_addc_u32 s39, s63, 0
	s_and_b32 s9, s98, 7
	s_lshl_b32 s9, s9, 8
	v_add_u32_e32 v1, s9, v48
	v_lshlrev_b32_e32 v28, 4, v1
	v_and_b32_e32 v2, 15, v1
	v_lshlrev_b32_e32 v2, 12, v2
	v_lshrrev_b32_e32 v4, 4, v1
	v_lshl_add_u32 v29, v4, 2, v2
	v_mov_b32_e32 v16, 0
	v_mov_b32_e32 v17, 0
	v_mov_b32_e32 v18, 0
	v_mov_b32_e32 v19, 0
	v_mov_b32_e32 v20, 0
	v_mov_b32_e32 v21, 0
	v_mov_b32_e32 v22, 0
	v_mov_b32_e32 v23, 0
	global_load_dwordx4 v[64:67], v28, s[34:35] nt
	s_add_u32 s34, s34, 0x20000
	s_addc_u32 s35, s35, 0
	global_load_dwordx4 v[68:71], v28, s[34:35] nt
	s_add_u32 s34, s34, 0x20000
	s_addc_u32 s35, s35, 0
	global_load_dwordx4 v[72:75], v28, s[34:35] nt
	s_add_u32 s34, s34, 0x20000
	s_addc_u32 s35, s35, 0
	global_load_dwordx4 v[76:79], v28, s[34:35] nt
	s_add_u32 s34, s34, 0x20000
	s_addc_u32 s35, s35, 0
	global_load_dwordx4 v[80:83], v28, s[34:35] nt
	s_add_u32 s34, s34, 0x20000
	s_addc_u32 s35, s35, 0
	global_load_dwordx4 v[84:87], v28, s[34:35] nt
	s_add_u32 s34, s34, 0x20000
	s_addc_u32 s35, s35, 0
	global_load_dwordx4 v[88:91], v28, s[34:35] nt
	s_add_u32 s34, s34, 0x20000
	s_addc_u32 s35, s35, 0
	global_load_dwordx4 v[92:95], v28, s[34:35] nt
	s_add_u32 s34, s34, 0x20000
	s_addc_u32 s35, s35, 0
	global_load_dwordx4 v[96:99], v28, s[34:35] nt
	s_add_u32 s34, s34, 0x20000
	s_addc_u32 s35, s35, 0
	global_load_dwordx4 v[100:103], v28, s[34:35] nt
	s_add_u32 s34, s34, 0x20000
	s_addc_u32 s35, s35, 0
	global_load_dwordx4 v[104:107], v28, s[34:35] nt
	s_add_u32 s34, s34, 0x20000
	s_addc_u32 s35, s35, 0
	global_load_dwordx4 v[108:111], v28, s[34:35] nt
	s_add_u32 s34, s34, 0x20000
	s_addc_u32 s35, s35, 0
	global_load_dwordx4 v[112:115], v28, s[34:35] nt
	s_add_u32 s34, s34, 0x20000
	s_addc_u32 s35, s35, 0
	global_load_dwordx4 v[116:119], v28, s[34:35] nt
	s_add_u32 s34, s34, 0x20000
	s_addc_u32 s35, s35, 0
	global_load_dwordx4 v[120:123], v28, s[34:35] nt
	s_add_u32 s34, s34, 0x20000
	s_addc_u32 s35, s35, 0
	global_load_dwordx4 v[124:127], v28, s[34:35] nt
	s_add_u32 s34, s34, 0x20000
	s_addc_u32 s35, s35, 0
	s_waitcnt vmcnt(15)
	v_lshlrev_b32_e32 v32, 16, v64
	v_and_b32_e32 v33, 0xffff0000, v64
	v_lshlrev_b32_e32 v34, 16, v65
	v_and_b32_e32 v35, 0xffff0000, v65
	v_lshlrev_b32_e32 v36, 16, v66
	v_and_b32_e32 v37, 0xffff0000, v66
	v_lshlrev_b32_e32 v38, 16, v67
	v_and_b32_e32 v39, 0xffff0000, v67
	v_fma_f32 v16, v24, v16, v32
	v_fma_f32 v17, v24, v17, v33
	v_fma_f32 v18, v24, v18, v34
	v_fma_f32 v19, v24, v19, v35
	v_fma_f32 v20, v24, v20, v36
	v_fma_f32 v21, v24, v21, v37
	v_fma_f32 v22, v24, v22, v38
	v_fma_f32 v23, v24, v23, v39
	v_cvt_pk_bf16_f32 v40, v16, v17
	v_cvt_pk_bf16_f32 v41, v18, v19
	v_cvt_pk_bf16_f32 v42, v20, v21
	v_cvt_pk_bf16_f32 v43, v22, v23
	global_store_dwordx4 v28, v[40:43], s[36:37]
	s_add_u32 s36, s36, 0x20000
	s_addc_u32 s37, s37, 0
	global_load_dwordx4 v[64:67], v28, s[34:35] nt
	s_add_u32 s34, s34, 0x20000
	s_addc_u32 s35, s35, 0
	s_waitcnt vmcnt(16)
	v_lshlrev_b32_e32 v32, 16, v68
	v_and_b32_e32 v33, 0xffff0000, v68
	v_lshlrev_b32_e32 v34, 16, v69
	v_and_b32_e32 v35, 0xffff0000, v69
	v_lshlrev_b32_e32 v36, 16, v70
	v_and_b32_e32 v37, 0xffff0000, v70
	v_lshlrev_b32_e32 v38, 16, v71
	v_and_b32_e32 v39, 0xffff0000, v71
	v_fma_f32 v16, v24, v16, v32
	v_fma_f32 v17, v24, v17, v33
	v_fma_f32 v18, v24, v18, v34
	v_fma_f32 v19, v24, v19, v35
	v_fma_f32 v20, v24, v20, v36
	v_fma_f32 v21, v24, v21, v37
	v_fma_f32 v22, v24, v22, v38
	v_fma_f32 v23, v24, v23, v39
	v_cvt_pk_bf16_f32 v44, v16, v17
	v_cvt_pk_bf16_f32 v45, v18, v19
	v_cvt_pk_bf16_f32 v46, v20, v21
	v_cvt_pk_bf16_f32 v47, v22, v23
	global_store_dwordx4 v28, v[44:47], s[36:37]
	s_add_u32 s36, s36, 0x20000
	s_addc_u32 s37, s37, 0
	global_load_dwordx4 v[68:71], v28, s[34:35] nt
	s_add_u32 s34, s34, 0x20000
	s_addc_u32 s35, s35, 0
	s_waitcnt vmcnt(17)
	v_lshlrev_b32_e32 v32, 16, v72
	v_and_b32_e32 v33, 0xffff0000, v72
	v_lshlrev_b32_e32 v34, 16, v73
	v_and_b32_e32 v35, 0xffff0000, v73
	v_lshlrev_b32_e32 v36, 16, v74
	v_and_b32_e32 v37, 0xffff0000, v74
	v_lshlrev_b32_e32 v38, 16, v75
	v_and_b32_e32 v39, 0xffff0000, v75
	v_fma_f32 v16, v24, v16, v32
	v_fma_f32 v17, v24, v17, v33
	v_fma_f32 v18, v24, v18, v34
	v_fma_f32 v19, v24, v19, v35
	v_fma_f32 v20, v24, v20, v36
	v_fma_f32 v21, v24, v21, v37
	v_fma_f32 v22, v24, v22, v38
	v_fma_f32 v23, v24, v23, v39
	v_cvt_pk_bf16_f32 v40, v16, v17
	v_cvt_pk_bf16_f32 v41, v18, v19
	v_cvt_pk_bf16_f32 v42, v20, v21
	v_cvt_pk_bf16_f32 v43, v22, v23
	global_store_dwordx4 v28, v[40:43], s[36:37]
	s_add_u32 s36, s36, 0x20000
	s_addc_u32 s37, s37, 0
	global_load_dwordx4 v[72:75], v28, s[34:35] nt
	s_add_u32 s34, s34, 0x20000
	s_addc_u32 s35, s35, 0
	s_waitcnt vmcnt(18)
; DI unsigned pk(float a, float b) { f32x2 v = {a, b}; bf16x2_t r = __builtin_convertvector(v, bf16x2_t); return __builtin_bit_cast(unsigned, r); }
; DI float bflo(unsigned u) { return __uint_as_float(u << 16); }
; DI float bfhi(unsigned u) { return __uint_as_float(u & 0xffff0000u); }
; DI void ret_scan(const Params& P, int G, int bx, int tid) {
;     ...
; #pragma unroll 8
;         for (int c = 0; c < 32; ++c) {
;             const size_t o = ((size_t)(b * 32 + c) * 4 + h) * 16384 + e4;
;             const u32x2 ub = __builtin_nontemporal_load((const u32x2*)(US + o));
;             s = s * g64 + (f32x4){bflo(ub.x), bfhi(ub.x), bflo(ub.y), bfhi(ub.y)};
;             u32x2 w = {pk(s[0], s[1]), pk(s[2], s[3])};
;             *(u32x2*)(SB + o) = w;
;         }
	v_lshlrev_b32_e32 v32, 16, v76
	v_and_b32_e32 v33, 0xffff0000, v76
	v_lshlrev_b32_e32 v34, 16, v77
	v_and_b32_e32 v35, 0xffff0000, v77
	v_lshlrev_b32_e32 v36, 16, v78
	v_and_b32_e32 v37, 0xffff0000, v78
	v_lshlrev_b32_e32 v38, 16, v79
	v_and_b32_e32 v39, 0xffff0000, v79
	v_fma_f32 v16, v24, v16, v32
	v_fma_f32 v17, v24, v17, v33
	v_fma_f32 v18, v24, v18, v34
	v_fma_f32 v19, v24, v19, v35
	v_fma_f32 v20, v24, v20, v36
	v_fma_f32 v21, v24, v21, v37
	v_fma_f32 v22, v24, v22, v38
	v_fma_f32 v23, v24, v23, v39
	v_cvt_pk_bf16_f32 v44, v16, v17
	v_cvt_pk_bf16_f32 v45, v18, v19
	v_cvt_pk_bf16_f32 v46, v20, v21
	v_cvt_pk_bf16_f32 v47, v22, v23
	global_store_dwordx4 v28, v[44:47], s[36:37]
	s_add_u32 s36, s36, 0x20000
	s_addc_u32 s37, s37, 0
	global_load_dwordx4 v[76:79], v28, s[34:35] nt
	s_add_u32 s34, s34, 0x20000
	s_addc_u32 s35, s35, 0
	s_waitcnt vmcnt(19)
	v_lshlrev_b32_e32 v32, 16, v80
	v_and_b32_e32 v33, 0xffff0000, v80
	v_lshlrev_b32_e32 v34, 16, v81
	v_and_b32_e32 v35, 0xffff0000, v81
	v_lshlrev_b32_e32 v36, 16, v82
	v_and_b32_e32 v37, 0xffff0000, v82
	v_lshlrev_b32_e32 v38, 16, v83
	v_and_b32_e32 v39, 0xffff0000, v83
	v_fma_f32 v16, v24, v16, v32
	v_fma_f32 v17, v24, v17, v33
	v_fma_f32 v18, v24, v18, v34
	v_fma_f32 v19, v24, v19, v35
	v_fma_f32 v20, v24, v20, v36
	v_fma_f32 v21, v24, v21, v37
	v_fma_f32 v22, v24, v22, v38
	v_fma_f32 v23, v24, v23, v39
	v_cvt_pk_bf16_f32 v40, v16, v17
	v_cvt_pk_bf16_f32 v41, v18, v19
	v_cvt_pk_bf16_f32 v42, v20, v21
	v_cvt_pk_bf16_f32 v43, v22, v23
	global_store_dwordx4 v28, v[40:43], s[36:37]
	s_add_u32 s36, s36, 0x20000
	s_addc_u32 s37, s37, 0
	global_load_dwordx4 v[80:83], v28, s[34:35] nt
	s_add_u32 s34, s34, 0x20000
	s_addc_u32 s35, s35, 0
	s_waitcnt vmcnt(20)
	v_lshlrev_b32_e32 v32, 16, v84
	v_and_b32_e32 v33, 0xffff0000, v84
	v_lshlrev_b32_e32 v34, 16, v85
	v_and_b32_e32 v35, 0xffff0000, v85
	v_lshlrev_b32_e32 v36, 16, v86
	v_and_b32_e32 v37, 0xffff0000, v86
	v_lshlrev_b32_e32 v38, 16, v87
	v_and_b32_e32 v39, 0xffff0000, v87
	v_fma_f32 v16, v24, v16, v32
	v_fma_f32 v17, v24, v17, v33
	v_fma_f32 v18, v24, v18, v34
	v_fma_f32 v19, v24, v19, v35
	v_fma_f32 v20, v24, v20, v36
	v_fma_f32 v21, v24, v21, v37
	v_fma_f32 v22, v24, v22, v38
	v_fma_f32 v23, v24, v23, v39
	v_cvt_pk_bf16_f32 v44, v16, v17
	v_cvt_pk_bf16_f32 v45, v18, v19
	v_cvt_pk_bf16_f32 v46, v20, v21
	v_cvt_pk_bf16_f32 v47, v22, v23
	global_store_dwordx4 v28, v[44:47], s[36:37]
	s_add_u32 s36, s36, 0x20000
	s_addc_u32 s37, s37, 0
	global_load_dwordx4 v[84:87], v28, s[34:35] nt
	s_add_u32 s34, s34, 0x20000
	s_addc_u32 s35, s35, 0
	s_waitcnt vmcnt(21)
	v_lshlrev_b32_e32 v32, 16, v88
	v_and_b32_e32 v33, 0xffff0000, v88
	v_lshlrev_b32_e32 v34, 16, v89
	v_and_b32_e32 v35, 0xffff0000, v89
	v_lshlrev_b32_e32 v36, 16, v90
	v_and_b32_e32 v37, 0xffff0000, v90
	v_lshlrev_b32_e32 v38, 16, v91
	v_and_b32_e32 v39, 0xffff0000, v91
	v_fma_f32 v16, v24, v16, v32
	v_fma_f32 v17, v24, v17, v33
	v_fma_f32 v18, v24, v18, v34
	v_fma_f32 v19, v24, v19, v35
	v_fma_f32 v20, v24, v20, v36
	v_fma_f32 v21, v24, v21, v37
	v_fma_f32 v22, v24, v22, v38
	v_fma_f32 v23, v24, v23, v39
	v_cvt_pk_bf16_f32 v40, v16, v17
	v_cvt_pk_bf16_f32 v41, v18, v19
	v_cvt_pk_bf16_f32 v42, v20, v21
	v_cvt_pk_bf16_f32 v43, v22, v23
	global_store_dwordx4 v28, v[40:43], s[36:37]
	s_add_u32 s36, s36, 0x20000
	s_addc_u32 s37, s37, 0
	global_load_dwordx4 v[88:91], v28, s[34:35] nt
	s_add_u32 s34, s34, 0x20000
	s_addc_u32 s35, s35, 0
	s_waitcnt vmcnt(22)
	v_lshlrev_b32_e32 v32, 16, v92
	v_and_b32_e32 v33, 0xffff0000, v92
	v_lshlrev_b32_e32 v34, 16, v93
	v_and_b32_e32 v35, 0xffff0000, v93
	v_lshlrev_b32_e32 v36, 16, v94
	v_and_b32_e32 v37, 0xffff0000, v94
	v_lshlrev_b32_e32 v38, 16, v95
	v_and_b32_e32 v39, 0xffff0000, v95
	v_fma_f32 v16, v24, v16, v32
	v_fma_f32 v17, v24, v17, v33
	v_fma_f32 v18, v24, v18, v34
	v_fma_f32 v19, v24, v19, v35
	v_fma_f32 v20, v24, v20, v36
	v_fma_f32 v21, v24, v21, v37
	v_fma_f32 v22, v24, v22, v38
	v_fma_f32 v23, v24, v23, v39
	v_cvt_pk_bf16_f32 v44, v16, v17
	v_cvt_pk_bf16_f32 v45, v18, v19
	v_cvt_pk_bf16_f32 v46, v20, v21
	v_cvt_pk_bf16_f32 v47, v22, v23
	global_store_dwordx4 v28, v[44:47], s[36:37]
	s_add_u32 s36, s36, 0x20000
	s_addc_u32 s37, s37, 0
	global_load_dwordx4 v[92:95], v28, s[34:35] nt
	s_add_u32 s34, s34, 0x20000
	s_addc_u32 s35, s35, 0
	s_waitcnt vmcnt(23)
	v_lshlrev_b32_e32 v32, 16, v96
	v_and_b32_e32 v33, 0xffff0000, v96
	v_lshlrev_b32_e32 v34, 16, v97
	v_and_b32_e32 v35, 0xffff0000, v97
	v_lshlrev_b32_e32 v36, 16, v98
	v_and_b32_e32 v37, 0xffff0000, v98
	v_lshlrev_b32_e32 v38, 16, v99
	v_and_b32_e32 v39, 0xffff0000, v99
	v_fma_f32 v16, v24, v16, v32
	v_fma_f32 v17, v24, v17, v33
	v_fma_f32 v18, v24, v18, v34
	v_fma_f32 v19, v24, v19, v35
	v_fma_f32 v20, v24, v20, v36
	v_fma_f32 v21, v24, v21, v37
	v_fma_f32 v22, v24, v22, v38
	v_fma_f32 v23, v24, v23, v39
	v_cvt_pk_bf16_f32 v40, v16, v17
	v_cvt_pk_bf16_f32 v41, v18, v19
	v_cvt_pk_bf16_f32 v42, v20, v21
	v_cvt_pk_bf16_f32 v43, v22, v23
	global_store_dwordx4 v28, v[40:43], s[36:37]
	s_add_u32 s36, s36, 0x20000
	s_addc_u32 s37, s37, 0
	global_load_dwordx4 v[96:99], v28, s[34:35] nt
	s_add_u32 s34, s34, 0x20000
	s_addc_u32 s35, s35, 0
	s_waitcnt vmcnt(24)
	v_lshlrev_b32_e32 v32, 16, v100
	v_and_b32_e32 v33, 0xffff0000, v100
	v_lshlrev_b32_e32 v34, 16, v101
	v_and_b32_e32 v35, 0xffff0000, v101
	v_lshlrev_b32_e32 v36, 16, v102
	v_and_b32_e32 v37, 0xffff0000, v102
	v_lshlrev_b32_e32 v38, 16, v103
	v_and_b32_e32 v39, 0xffff0000, v103
	v_fma_f32 v16, v24, v16, v32
	v_fma_f32 v17, v24, v17, v33
	v_fma_f32 v18, v24, v18, v34
	v_fma_f32 v19, v24, v19, v35
	v_fma_f32 v20, v24, v20, v36
	v_fma_f32 v21, v24, v21, v37
	v_fma_f32 v22, v24, v22, v38
	v_fma_f32 v23, v24, v23, v39
	v_cvt_pk_bf16_f32 v44, v16, v17
	v_cvt_pk_bf16_f32 v45, v18, v19
	v_cvt_pk_bf16_f32 v46, v20, v21
	v_cvt_pk_bf16_f32 v47, v22, v23
	global_store_dwordx4 v28, v[44:47], s[36:37]
	s_add_u32 s36, s36, 0x20000
	s_addc_u32 s37, s37, 0
	global_load_dwordx4 v[100:103], v28, s[34:35] nt
	s_add_u32 s34, s34, 0x20000
	s_addc_u32 s35, s35, 0
	s_waitcnt vmcnt(25)
; DI unsigned pk(float a, float b) { f32x2 v = {a, b}; bf16x2_t r = __builtin_convertvector(v, bf16x2_t); return __builtin_bit_cast(unsigned, r); }
; DI float bflo(unsigned u) { return __uint_as_float(u << 16); }
; DI float bfhi(unsigned u) { return __uint_as_float(u & 0xffff0000u); }
; DI void ret_scan(const Params& P, int G, int bx, int tid) {
;     ...
; #pragma unroll 8
;         for (int c = 0; c < 32; ++c) {
;             const size_t o = ((size_t)(b * 32 + c) * 4 + h) * 16384 + e4;
;             const u32x2 ub = __builtin_nontemporal_load((const u32x2*)(US + o));
;             s = s * g64 + (f32x4){bflo(ub.x), bfhi(ub.x), bflo(ub.y), bfhi(ub.y)};
;             u32x2 w = {pk(s[0], s[1]), pk(s[2], s[3])};
;             *(u32x2*)(SB + o) = w;
;         }
	v_lshlrev_b32_e32 v32, 16, v104
	v_and_b32_e32 v33, 0xffff0000, v104
	v_lshlrev_b32_e32 v34, 16, v105
	v_and_b32_e32 v35, 0xffff0000, v105
	v_lshlrev_b32_e32 v36, 16, v106
	v_and_b32_e32 v37, 0xffff0000, v106
	v_lshlrev_b32_e32 v38, 16, v107
	v_and_b32_e32 v39, 0xffff0000, v107
	v_fma_f32 v16, v24, v16, v32
	v_fma_f32 v17, v24, v17, v33
	v_fma_f32 v18, v24, v18, v34
	v_fma_f32 v19, v24, v19, v35
	v_fma_f32 v20, v24, v20, v36
	v_fma_f32 v21, v24, v21, v37
	v_fma_f32 v22, v24, v22, v38
	v_fma_f32 v23, v24, v23, v39
	v_cvt_pk_bf16_f32 v40, v16, v17
	v_cvt_pk_bf16_f32 v41, v18, v19
	v_cvt_pk_bf16_f32 v42, v20, v21
	v_cvt_pk_bf16_f32 v43, v22, v23
	global_store_dwordx4 v28, v[40:43], s[36:37]
	s_add_u32 s36, s36, 0x20000
	s_addc_u32 s37, s37, 0
	global_load_dwordx4 v[104:107], v28, s[34:35] nt
	s_add_u32 s34, s34, 0x20000
	s_addc_u32 s35, s35, 0
	s_waitcnt vmcnt(26)
	v_lshlrev_b32_e32 v32, 16, v108
	v_and_b32_e32 v33, 0xffff0000, v108
	v_lshlrev_b32_e32 v34, 16, v109
	v_and_b32_e32 v35, 0xffff0000, v109
	v_lshlrev_b32_e32 v36, 16, v110
	v_and_b32_e32 v37, 0xffff0000, v110
	v_lshlrev_b32_e32 v38, 16, v111
	v_and_b32_e32 v39, 0xffff0000, v111
	v_fma_f32 v16, v24, v16, v32
	v_fma_f32 v17, v24, v17, v33
	v_fma_f32 v18, v24, v18, v34
	v_fma_f32 v19, v24, v19, v35
	v_fma_f32 v20, v24, v20, v36
	v_fma_f32 v21, v24, v21, v37
	v_fma_f32 v22, v24, v22, v38
	v_fma_f32 v23, v24, v23, v39
	v_cvt_pk_bf16_f32 v44, v16, v17
	v_cvt_pk_bf16_f32 v45, v18, v19
	v_cvt_pk_bf16_f32 v46, v20, v21
	v_cvt_pk_bf16_f32 v47, v22, v23
	global_store_dwordx4 v28, v[44:47], s[36:37]
	s_add_u32 s36, s36, 0x20000
	s_addc_u32 s37, s37, 0
	global_load_dwordx4 v[108:111], v28, s[34:35] nt
	s_add_u32 s34, s34, 0x20000
	s_addc_u32 s35, s35, 0
	s_waitcnt vmcnt(27)
	v_lshlrev_b32_e32 v32, 16, v112
	v_and_b32_e32 v33, 0xffff0000, v112
	v_lshlrev_b32_e32 v34, 16, v113
	v_and_b32_e32 v35, 0xffff0000, v113
	v_lshlrev_b32_e32 v36, 16, v114
	v_and_b32_e32 v37, 0xffff0000, v114
	v_lshlrev_b32_e32 v38, 16, v115
	v_and_b32_e32 v39, 0xffff0000, v115
	v_fma_f32 v16, v24, v16, v32
	v_fma_f32 v17, v24, v17, v33
	v_fma_f32 v18, v24, v18, v34
	v_fma_f32 v19, v24, v19, v35
	v_fma_f32 v20, v24, v20, v36
	v_fma_f32 v21, v24, v21, v37
	v_fma_f32 v22, v24, v22, v38
	v_fma_f32 v23, v24, v23, v39
	v_cvt_pk_bf16_f32 v40, v16, v17
	v_cvt_pk_bf16_f32 v41, v18, v19
	v_cvt_pk_bf16_f32 v42, v20, v21
	v_cvt_pk_bf16_f32 v43, v22, v23
	global_store_dwordx4 v28, v[40:43], s[36:37]
	s_add_u32 s36, s36, 0x20000
	s_addc_u32 s37, s37, 0
	global_load_dwordx4 v[112:115], v28, s[34:35] nt
	s_add_u32 s34, s34, 0x20000
	s_addc_u32 s35, s35, 0
	s_waitcnt vmcnt(28)
	v_lshlrev_b32_e32 v32, 16, v116
	v_and_b32_e32 v33, 0xffff0000, v116
	v_lshlrev_b32_e32 v34, 16, v117
	v_and_b32_e32 v35, 0xffff0000, v117
	v_lshlrev_b32_e32 v36, 16, v118
	v_and_b32_e32 v37, 0xffff0000, v118
	v_lshlrev_b32_e32 v38, 16, v119
	v_and_b32_e32 v39, 0xffff0000, v119
	v_fma_f32 v16, v24, v16, v32
	v_fma_f32 v17, v24, v17, v33
	v_fma_f32 v18, v24, v18, v34
	v_fma_f32 v19, v24, v19, v35
	v_fma_f32 v20, v24, v20, v36
	v_fma_f32 v21, v24, v21, v37
	v_fma_f32 v22, v24, v22, v38
	v_fma_f32 v23, v24, v23, v39
	v_cvt_pk_bf16_f32 v44, v16, v17
	v_cvt_pk_bf16_f32 v45, v18, v19
	v_cvt_pk_bf16_f32 v46, v20, v21
	v_cvt_pk_bf16_f32 v47, v22, v23
	global_store_dwordx4 v28, v[44:47], s[36:37]
	s_add_u32 s36, s36, 0x20000
	s_addc_u32 s37, s37, 0
	global_load_dwordx4 v[116:119], v28, s[34:35] nt
	s_add_u32 s34, s34, 0x20000
	s_addc_u32 s35, s35, 0
	s_waitcnt vmcnt(29)
	v_lshlrev_b32_e32 v32, 16, v120
	v_and_b32_e32 v33, 0xffff0000, v120
	v_lshlrev_b32_e32 v34, 16, v121
	v_and_b32_e32 v35, 0xffff0000, v121
	v_lshlrev_b32_e32 v36, 16, v122
	v_and_b32_e32 v37, 0xffff0000, v122
	v_lshlrev_b32_e32 v38, 16, v123
	v_and_b32_e32 v39, 0xffff0000, v123
	v_fma_f32 v16, v24, v16, v32
	v_fma_f32 v17, v24, v17, v33
	v_fma_f32 v18, v24, v18, v34
	v_fma_f32 v19, v24, v19, v35
	v_fma_f32 v20, v24, v20, v36
	v_fma_f32 v21, v24, v21, v37
	v_fma_f32 v22, v24, v22, v38
	v_fma_f32 v23, v24, v23, v39
	v_cvt_pk_bf16_f32 v40, v16, v17
	v_cvt_pk_bf16_f32 v41, v18, v19
	v_cvt_pk_bf16_f32 v42, v20, v21
	v_cvt_pk_bf16_f32 v43, v22, v23
	global_store_dwordx4 v28, v[40:43], s[36:37]
	s_add_u32 s36, s36, 0x20000
	s_addc_u32 s37, s37, 0
	global_load_dwordx4 v[120:123], v28, s[34:35] nt
	s_add_u32 s34, s34, 0x20000
	s_addc_u32 s35, s35, 0
	s_waitcnt vmcnt(30)
	v_lshlrev_b32_e32 v32, 16, v124
	v_and_b32_e32 v33, 0xffff0000, v124
	v_lshlrev_b32_e32 v34, 16, v125
	v_and_b32_e32 v35, 0xffff0000, v125
	v_lshlrev_b32_e32 v36, 16, v126
	v_and_b32_e32 v37, 0xffff0000, v126
	v_lshlrev_b32_e32 v38, 16, v127
	v_and_b32_e32 v39, 0xffff0000, v127
	v_fma_f32 v16, v24, v16, v32
	v_fma_f32 v17, v24, v17, v33
	v_fma_f32 v18, v24, v18, v34
	v_fma_f32 v19, v24, v19, v35
	v_fma_f32 v20, v24, v20, v36
	v_fma_f32 v21, v24, v21, v37
	v_fma_f32 v22, v24, v22, v38
	v_fma_f32 v23, v24, v23, v39
	v_cvt_pk_bf16_f32 v44, v16, v17
	v_cvt_pk_bf16_f32 v45, v18, v19
	v_cvt_pk_bf16_f32 v46, v20, v21
	v_cvt_pk_bf16_f32 v47, v22, v23
	global_store_dwordx4 v28, v[44:47], s[36:37]
	s_add_u32 s36, s36, 0x20000
	s_addc_u32 s37, s37, 0
	global_load_dwordx4 v[124:127], v28, s[34:35] nt
	s_add_u32 s34, s34, 0x20000
	s_addc_u32 s35, s35, 0
	s_waitcnt vmcnt(30)
	v_lshlrev_b32_e32 v32, 16, v64
	v_and_b32_e32 v33, 0xffff0000, v64
	v_lshlrev_b32_e32 v34, 16, v65
	v_and_b32_e32 v35, 0xffff0000, v65
	v_lshlrev_b32_e32 v36, 16, v66
	v_and_b32_e32 v37, 0xffff0000, v66
	v_lshlrev_b32_e32 v38, 16, v67
	v_and_b32_e32 v39, 0xffff0000, v67
	v_fma_f32 v16, v24, v16, v32
	v_fma_f32 v17, v24, v17, v33
	v_fma_f32 v18, v24, v18, v34
	v_fma_f32 v19, v24, v19, v35
	v_fma_f32 v20, v24, v20, v36
	v_fma_f32 v21, v24, v21, v37
	v_fma_f32 v22, v24, v22, v38
	v_fma_f32 v23, v24, v23, v39
	v_cvt_pk_bf16_f32 v40, v16, v17
	v_cvt_pk_bf16_f32 v41, v18, v19
	v_cvt_pk_bf16_f32 v42, v20, v21
	v_cvt_pk_bf16_f32 v43, v22, v23
	global_store_dwordx4 v28, v[40:43], s[36:37]
	s_add_u32 s36, s36, 0x20000
	s_addc_u32 s37, s37, 0
	s_waitcnt vmcnt(29)
; DI unsigned pk(float a, float b) { f32x2 v = {a, b}; bf16x2_t r = __builtin_convertvector(v, bf16x2_t); return __builtin_bit_cast(unsigned, r); }
; DI float bflo(unsigned u) { return __uint_as_float(u << 16); }
; DI float bfhi(unsigned u) { return __uint_as_float(u & 0xffff0000u); }
; DI void ret_scan(const Params& P, int G, int bx, int tid) {
;     ...
;         for (int c = 0; c < 32; ++c) {
;             const size_t o = ((size_t)(b * 32 + c) * 4 + h) * 16384 + e4;
;             const u32x2 ub = __builtin_nontemporal_load((const u32x2*)(US + o));
;             s = s * g64 + (f32x4){bflo(ub.x), bfhi(ub.x), bflo(ub.y), bfhi(ub.y)};
;             u32x2 w = {pk(s[0], s[1]), pk(s[2], s[3])};
;             *(u32x2*)(SB + o) = w;
;         }
	v_lshlrev_b32_e32 v32, 16, v68
	v_and_b32_e32 v33, 0xffff0000, v68
	v_lshlrev_b32_e32 v34, 16, v69
	v_and_b32_e32 v35, 0xffff0000, v69
	v_lshlrev_b32_e32 v36, 16, v70
	v_and_b32_e32 v37, 0xffff0000, v70
	v_lshlrev_b32_e32 v38, 16, v71
	v_and_b32_e32 v39, 0xffff0000, v71
	v_fma_f32 v16, v24, v16, v32
	v_fma_f32 v17, v24, v17, v33
	v_fma_f32 v18, v24, v18, v34
	v_fma_f32 v19, v24, v19, v35
	v_fma_f32 v20, v24, v20, v36
	v_fma_f32 v21, v24, v21, v37
	v_fma_f32 v22, v24, v22, v38
	v_fma_f32 v23, v24, v23, v39
	v_cvt_pk_bf16_f32 v44, v16, v17
	v_cvt_pk_bf16_f32 v45, v18, v19
	v_cvt_pk_bf16_f32 v46, v20, v21
	v_cvt_pk_bf16_f32 v47, v22, v23
	global_store_dwordx4 v28, v[44:47], s[36:37]
	s_add_u32 s36, s36, 0x20000
	s_addc_u32 s37, s37, 0
	s_waitcnt vmcnt(28)
	v_lshlrev_b32_e32 v32, 16, v72
	v_and_b32_e32 v33, 0xffff0000, v72
	v_lshlrev_b32_e32 v34, 16, v73
	v_and_b32_e32 v35, 0xffff0000, v73
	v_lshlrev_b32_e32 v36, 16, v74
	v_and_b32_e32 v37, 0xffff0000, v74
	v_lshlrev_b32_e32 v38, 16, v75
	v_and_b32_e32 v39, 0xffff0000, v75
	v_fma_f32 v16, v24, v16, v32
	v_fma_f32 v17, v24, v17, v33
	v_fma_f32 v18, v24, v18, v34
	v_fma_f32 v19, v24, v19, v35
	v_fma_f32 v20, v24, v20, v36
	v_fma_f32 v21, v24, v21, v37
	v_fma_f32 v22, v24, v22, v38
	v_fma_f32 v23, v24, v23, v39
	v_cvt_pk_bf16_f32 v40, v16, v17
	v_cvt_pk_bf16_f32 v41, v18, v19
	v_cvt_pk_bf16_f32 v42, v20, v21
	v_cvt_pk_bf16_f32 v43, v22, v23
	global_store_dwordx4 v28, v[40:43], s[36:37]
	s_add_u32 s36, s36, 0x20000
	s_addc_u32 s37, s37, 0
	s_waitcnt vmcnt(27)
	v_lshlrev_b32_e32 v32, 16, v76
	v_and_b32_e32 v33, 0xffff0000, v76
	v_lshlrev_b32_e32 v34, 16, v77
	v_and_b32_e32 v35, 0xffff0000, v77
	v_lshlrev_b32_e32 v36, 16, v78
	v_and_b32_e32 v37, 0xffff0000, v78
	v_lshlrev_b32_e32 v38, 16, v79
	v_and_b32_e32 v39, 0xffff0000, v79
	v_fma_f32 v16, v24, v16, v32
	v_fma_f32 v17, v24, v17, v33
	v_fma_f32 v18, v24, v18, v34
	v_fma_f32 v19, v24, v19, v35
	v_fma_f32 v20, v24, v20, v36
	v_fma_f32 v21, v24, v21, v37
	v_fma_f32 v22, v24, v22, v38
	v_fma_f32 v23, v24, v23, v39
	v_cvt_pk_bf16_f32 v44, v16, v17
	v_cvt_pk_bf16_f32 v45, v18, v19
	v_cvt_pk_bf16_f32 v46, v20, v21
	v_cvt_pk_bf16_f32 v47, v22, v23
	global_store_dwordx4 v28, v[44:47], s[36:37]
	s_add_u32 s36, s36, 0x20000
	s_addc_u32 s37, s37, 0
	s_waitcnt vmcnt(26)
	v_lshlrev_b32_e32 v32, 16, v80
	v_and_b32_e32 v33, 0xffff0000, v80
	v_lshlrev_b32_e32 v34, 16, v81
	v_and_b32_e32 v35, 0xffff0000, v81
	v_lshlrev_b32_e32 v36, 16, v82
	v_and_b32_e32 v37, 0xffff0000, v82
	v_lshlrev_b32_e32 v38, 16, v83
	v_and_b32_e32 v39, 0xffff0000, v83
	v_fma_f32 v16, v24, v16, v32
	v_fma_f32 v17, v24, v17, v33
	v_fma_f32 v18, v24, v18, v34
	v_fma_f32 v19, v24, v19, v35
	v_fma_f32 v20, v24, v20, v36
	v_fma_f32 v21, v24, v21, v37
	v_fma_f32 v22, v24, v22, v38
	v_fma_f32 v23, v24, v23, v39
	v_cvt_pk_bf16_f32 v40, v16, v17
	v_cvt_pk_bf16_f32 v41, v18, v19
	v_cvt_pk_bf16_f32 v42, v20, v21
	v_cvt_pk_bf16_f32 v43, v22, v23
	global_store_dwordx4 v28, v[40:43], s[36:37]
	s_add_u32 s36, s36, 0x20000
	s_addc_u32 s37, s37, 0
	s_waitcnt vmcnt(25)
	v_lshlrev_b32_e32 v32, 16, v84
	v_and_b32_e32 v33, 0xffff0000, v84
	v_lshlrev_b32_e32 v34, 16, v85
	v_and_b32_e32 v35, 0xffff0000, v85
	v_lshlrev_b32_e32 v36, 16, v86
	v_and_b32_e32 v37, 0xffff0000, v86
	v_lshlrev_b32_e32 v38, 16, v87
	v_and_b32_e32 v39, 0xffff0000, v87
	v_fma_f32 v16, v24, v16, v32
	v_fma_f32 v17, v24, v17, v33
	v_fma_f32 v18, v24, v18, v34
	v_fma_f32 v19, v24, v19, v35
	v_fma_f32 v20, v24, v20, v36
	v_fma_f32 v21, v24, v21, v37
	v_fma_f32 v22, v24, v22, v38
	v_fma_f32 v23, v24, v23, v39
	v_cvt_pk_bf16_f32 v44, v16, v17
	v_cvt_pk_bf16_f32 v45, v18, v19
	v_cvt_pk_bf16_f32 v46, v20, v21
	v_cvt_pk_bf16_f32 v47, v22, v23
	global_store_dwordx4 v28, v[44:47], s[36:37]
	s_add_u32 s36, s36, 0x20000
	s_addc_u32 s37, s37, 0
	s_waitcnt vmcnt(24)
	v_lshlrev_b32_e32 v32, 16, v88
	v_and_b32_e32 v33, 0xffff0000, v88
	v_lshlrev_b32_e32 v34, 16, v89
	v_and_b32_e32 v35, 0xffff0000, v89
	v_lshlrev_b32_e32 v36, 16, v90
	v_and_b32_e32 v37, 0xffff0000, v90
	v_lshlrev_b32_e32 v38, 16, v91
	v_and_b32_e32 v39, 0xffff0000, v91
	v_fma_f32 v16, v24, v16, v32
	v_fma_f32 v17, v24, v17, v33
	v_fma_f32 v18, v24, v18, v34
	v_fma_f32 v19, v24, v19, v35
	v_fma_f32 v20, v24, v20, v36
	v_fma_f32 v21, v24, v21, v37
	v_fma_f32 v22, v24, v22, v38
	v_fma_f32 v23, v24, v23, v39
	v_cvt_pk_bf16_f32 v40, v16, v17
	v_cvt_pk_bf16_f32 v41, v18, v19
	v_cvt_pk_bf16_f32 v42, v20, v21
	v_cvt_pk_bf16_f32 v43, v22, v23
	global_store_dwordx4 v28, v[40:43], s[36:37]
	s_add_u32 s36, s36, 0x20000
	s_addc_u32 s37, s37, 0
	s_waitcnt vmcnt(23)
	v_lshlrev_b32_e32 v32, 16, v92
	v_and_b32_e32 v33, 0xffff0000, v92
	v_lshlrev_b32_e32 v34, 16, v93
	v_and_b32_e32 v35, 0xffff0000, v93
	v_lshlrev_b32_e32 v36, 16, v94
	v_and_b32_e32 v37, 0xffff0000, v94
	v_lshlrev_b32_e32 v38, 16, v95
	v_and_b32_e32 v39, 0xffff0000, v95
	v_fma_f32 v16, v24, v16, v32
	v_fma_f32 v17, v24, v17, v33
	v_fma_f32 v18, v24, v18, v34
	v_fma_f32 v19, v24, v19, v35
	v_fma_f32 v20, v24, v20, v36
	v_fma_f32 v21, v24, v21, v37
	v_fma_f32 v22, v24, v22, v38
	v_fma_f32 v23, v24, v23, v39
	v_cvt_pk_bf16_f32 v44, v16, v17
	v_cvt_pk_bf16_f32 v45, v18, v19
	v_cvt_pk_bf16_f32 v46, v20, v21
	v_cvt_pk_bf16_f32 v47, v22, v23
	global_store_dwordx4 v28, v[44:47], s[36:37]
	s_add_u32 s36, s36, 0x20000
	s_addc_u32 s37, s37, 0
	s_waitcnt vmcnt(22)
; DI unsigned pk(float a, float b) { f32x2 v = {a, b}; bf16x2_t r = __builtin_convertvector(v, bf16x2_t); return __builtin_bit_cast(unsigned, r); }
; DI float bflo(unsigned u) { return __uint_as_float(u << 16); }
; DI float bfhi(unsigned u) { return __uint_as_float(u & 0xffff0000u); }
; DI void ret_scan(const Params& P, int G, int bx, int tid) {
;     ...
;         for (int c = 0; c < 32; ++c) {
;             const size_t o = ((size_t)(b * 32 + c) * 4 + h) * 16384 + e4;
;             const u32x2 ub = __builtin_nontemporal_load((const u32x2*)(US + o));
;             s = s * g64 + (f32x4){bflo(ub.x), bfhi(ub.x), bflo(ub.y), bfhi(ub.y)};
;             u32x2 w = {pk(s[0], s[1]), pk(s[2], s[3])};
;             *(u32x2*)(SB + o) = w;
;         }
;         const int e = e4 >> 7, dk = e4 & 127;
;         float* o = P.out + O_NRP + (size_t)bh * 16384 + e;
; #pragma unroll
;         for (int i = 0; i < 4; ++i) o[(dk + i) * 128] = s[i];
	v_lshlrev_b32_e32 v32, 16, v96
	v_and_b32_e32 v33, 0xffff0000, v96
	v_lshlrev_b32_e32 v34, 16, v97
	v_and_b32_e32 v35, 0xffff0000, v97
	v_lshlrev_b32_e32 v36, 16, v98
	v_and_b32_e32 v37, 0xffff0000, v98
	v_lshlrev_b32_e32 v38, 16, v99
	v_and_b32_e32 v39, 0xffff0000, v99
	v_fma_f32 v16, v24, v16, v32
	v_fma_f32 v17, v24, v17, v33
	v_fma_f32 v18, v24, v18, v34
	v_fma_f32 v19, v24, v19, v35
	v_fma_f32 v20, v24, v20, v36
	v_fma_f32 v21, v24, v21, v37
	v_fma_f32 v22, v24, v22, v38
	v_fma_f32 v23, v24, v23, v39
	v_cvt_pk_bf16_f32 v40, v16, v17
	v_cvt_pk_bf16_f32 v41, v18, v19
	v_cvt_pk_bf16_f32 v42, v20, v21
	v_cvt_pk_bf16_f32 v43, v22, v23
	global_store_dwordx4 v28, v[40:43], s[36:37]
	s_add_u32 s36, s36, 0x20000
	s_addc_u32 s37, s37, 0
	s_waitcnt vmcnt(21)
	v_lshlrev_b32_e32 v32, 16, v100
	v_and_b32_e32 v33, 0xffff0000, v100
	v_lshlrev_b32_e32 v34, 16, v101
	v_and_b32_e32 v35, 0xffff0000, v101
	v_lshlrev_b32_e32 v36, 16, v102
	v_and_b32_e32 v37, 0xffff0000, v102
	v_lshlrev_b32_e32 v38, 16, v103
	v_and_b32_e32 v39, 0xffff0000, v103
	v_fma_f32 v16, v24, v16, v32
	v_fma_f32 v17, v24, v17, v33
	v_fma_f32 v18, v24, v18, v34
	v_fma_f32 v19, v24, v19, v35
	v_fma_f32 v20, v24, v20, v36
	v_fma_f32 v21, v24, v21, v37
	v_fma_f32 v22, v24, v22, v38
	v_fma_f32 v23, v24, v23, v39
	v_cvt_pk_bf16_f32 v44, v16, v17
	v_cvt_pk_bf16_f32 v45, v18, v19
	v_cvt_pk_bf16_f32 v46, v20, v21
	v_cvt_pk_bf16_f32 v47, v22, v23
	global_store_dwordx4 v28, v[44:47], s[36:37]
	s_add_u32 s36, s36, 0x20000
	s_addc_u32 s37, s37, 0
	s_waitcnt vmcnt(20)
	v_lshlrev_b32_e32 v32, 16, v104
	v_and_b32_e32 v33, 0xffff0000, v104
	v_lshlrev_b32_e32 v34, 16, v105
	v_and_b32_e32 v35, 0xffff0000, v105
	v_lshlrev_b32_e32 v36, 16, v106
	v_and_b32_e32 v37, 0xffff0000, v106
	v_lshlrev_b32_e32 v38, 16, v107
	v_and_b32_e32 v39, 0xffff0000, v107
	v_fma_f32 v16, v24, v16, v32
	v_fma_f32 v17, v24, v17, v33
	v_fma_f32 v18, v24, v18, v34
	v_fma_f32 v19, v24, v19, v35
	v_fma_f32 v20, v24, v20, v36
	v_fma_f32 v21, v24, v21, v37
	v_fma_f32 v22, v24, v22, v38
	v_fma_f32 v23, v24, v23, v39
	v_cvt_pk_bf16_f32 v40, v16, v17
	v_cvt_pk_bf16_f32 v41, v18, v19
	v_cvt_pk_bf16_f32 v42, v20, v21
	v_cvt_pk_bf16_f32 v43, v22, v23
	global_store_dwordx4 v28, v[40:43], s[36:37]
	s_add_u32 s36, s36, 0x20000
	s_addc_u32 s37, s37, 0
	s_waitcnt vmcnt(19)
	v_lshlrev_b32_e32 v32, 16, v108
	v_and_b32_e32 v33, 0xffff0000, v108
	v_lshlrev_b32_e32 v34, 16, v109
	v_and_b32_e32 v35, 0xffff0000, v109
	v_lshlrev_b32_e32 v36, 16, v110
	v_and_b32_e32 v37, 0xffff0000, v110
	v_lshlrev_b32_e32 v38, 16, v111
	v_and_b32_e32 v39, 0xffff0000, v111
	v_fma_f32 v16, v24, v16, v32
	v_fma_f32 v17, v24, v17, v33
	v_fma_f32 v18, v24, v18, v34
	v_fma_f32 v19, v24, v19, v35
	v_fma_f32 v20, v24, v20, v36
	v_fma_f32 v21, v24, v21, v37
	v_fma_f32 v22, v24, v22, v38
	v_fma_f32 v23, v24, v23, v39
	v_cvt_pk_bf16_f32 v44, v16, v17
	v_cvt_pk_bf16_f32 v45, v18, v19
	v_cvt_pk_bf16_f32 v46, v20, v21
	v_cvt_pk_bf16_f32 v47, v22, v23
	global_store_dwordx4 v28, v[44:47], s[36:37]
	s_add_u32 s36, s36, 0x20000
	s_addc_u32 s37, s37, 0
	s_waitcnt vmcnt(18)
	v_lshlrev_b32_e32 v32, 16, v112
	v_and_b32_e32 v33, 0xffff0000, v112
	v_lshlrev_b32_e32 v34, 16, v113
	v_and_b32_e32 v35, 0xffff0000, v113
	v_lshlrev_b32_e32 v36, 16, v114
	v_and_b32_e32 v37, 0xffff0000, v114
	v_lshlrev_b32_e32 v38, 16, v115
	v_and_b32_e32 v39, 0xffff0000, v115
	v_fma_f32 v16, v24, v16, v32
	v_fma_f32 v17, v24, v17, v33
	v_fma_f32 v18, v24, v18, v34
	v_fma_f32 v19, v24, v19, v35
	v_fma_f32 v20, v24, v20, v36
	v_fma_f32 v21, v24, v21, v37
	v_fma_f32 v22, v24, v22, v38
	v_fma_f32 v23, v24, v23, v39
	v_cvt_pk_bf16_f32 v40, v16, v17
	v_cvt_pk_bf16_f32 v41, v18, v19
	v_cvt_pk_bf16_f32 v42, v20, v21
	v_cvt_pk_bf16_f32 v43, v22, v23
	global_store_dwordx4 v28, v[40:43], s[36:37]
	s_add_u32 s36, s36, 0x20000
	s_addc_u32 s37, s37, 0
	s_waitcnt vmcnt(17)
	v_lshlrev_b32_e32 v32, 16, v116
	v_and_b32_e32 v33, 0xffff0000, v116
	v_lshlrev_b32_e32 v34, 16, v117
	v_and_b32_e32 v35, 0xffff0000, v117
	v_lshlrev_b32_e32 v36, 16, v118
	v_and_b32_e32 v37, 0xffff0000, v118
	v_lshlrev_b32_e32 v38, 16, v119
	v_and_b32_e32 v39, 0xffff0000, v119
	v_fma_f32 v16, v24, v16, v32
	v_fma_f32 v17, v24, v17, v33
	v_fma_f32 v18, v24, v18, v34
	v_fma_f32 v19, v24, v19, v35
	v_fma_f32 v20, v24, v20, v36
	v_fma_f32 v21, v24, v21, v37
	v_fma_f32 v22, v24, v22, v38
	v_fma_f32 v23, v24, v23, v39
	v_cvt_pk_bf16_f32 v44, v16, v17
	v_cvt_pk_bf16_f32 v45, v18, v19
	v_cvt_pk_bf16_f32 v46, v20, v21
	v_cvt_pk_bf16_f32 v47, v22, v23
	global_store_dwordx4 v28, v[44:47], s[36:37]
	s_add_u32 s36, s36, 0x20000
	s_addc_u32 s37, s37, 0
	s_waitcnt vmcnt(16)
	v_lshlrev_b32_e32 v32, 16, v120
	v_and_b32_e32 v33, 0xffff0000, v120
	v_lshlrev_b32_e32 v34, 16, v121
	v_and_b32_e32 v35, 0xffff0000, v121
	v_lshlrev_b32_e32 v36, 16, v122
	v_and_b32_e32 v37, 0xffff0000, v122
	v_lshlrev_b32_e32 v38, 16, v123
	v_and_b32_e32 v39, 0xffff0000, v123
	v_fma_f32 v16, v24, v16, v32
	v_fma_f32 v17, v24, v17, v33
	v_fma_f32 v18, v24, v18, v34
	v_fma_f32 v19, v24, v19, v35
	v_fma_f32 v20, v24, v20, v36
	v_fma_f32 v21, v24, v21, v37
	v_fma_f32 v22, v24, v22, v38
	v_fma_f32 v23, v24, v23, v39
	v_cvt_pk_bf16_f32 v40, v16, v17
	v_cvt_pk_bf16_f32 v41, v18, v19
	v_cvt_pk_bf16_f32 v42, v20, v21
	v_cvt_pk_bf16_f32 v43, v22, v23
	global_store_dwordx4 v28, v[40:43], s[36:37]
	s_add_u32 s36, s36, 0x20000
	s_addc_u32 s37, s37, 0
	s_waitcnt vmcnt(15)
	v_lshlrev_b32_e32 v32, 16, v124
	v_and_b32_e32 v33, 0xffff0000, v124
	v_lshlrev_b32_e32 v34, 16, v125
	v_and_b32_e32 v35, 0xffff0000, v125
	v_lshlrev_b32_e32 v36, 16, v126
	v_and_b32_e32 v37, 0xffff0000, v126
	v_lshlrev_b32_e32 v38, 16, v127
	v_and_b32_e32 v39, 0xffff0000, v127
	v_fma_f32 v16, v24, v16, v32
	v_fma_f32 v17, v24, v17, v33
	v_fma_f32 v18, v24, v18, v34
	v_fma_f32 v19, v24, v19, v35
	v_fma_f32 v20, v24, v20, v36
	v_fma_f32 v21, v24, v21, v37
	v_fma_f32 v22, v24, v22, v38
	v_fma_f32 v23, v24, v23, v39
	v_cvt_pk_bf16_f32 v44, v16, v17
	v_cvt_pk_bf16_f32 v45, v18, v19
	v_cvt_pk_bf16_f32 v46, v20, v21
	v_cvt_pk_bf16_f32 v47, v22, v23
	global_store_dwordx4 v28, v[44:47], s[36:37]
	s_add_u32 s36, s36, 0x20000
	s_addc_u32 s37, s37, 0
	global_store_dword v29, v16, s[38:39]
	global_store_dword v29, v17, s[38:39] offset:512
	global_store_dword v29, v18, s[38:39] offset:1024
	global_store_dword v29, v19, s[38:39] offset:1536
	global_store_dword v29, v20, s[38:39] offset:2048
	global_store_dword v29, v21, s[38:39] offset:2560
	global_store_dword v29, v22, s[38:39] offset:3072
	global_store_dword v29, v23, s[38:39] offset:3584
; DI int lane_id() { return (int)__builtin_amdgcn_mbcnt_hi(~0u, __builtin_amdgcn_mbcnt_lo(~0u, 0u)); }
; __device__ __forceinline__ unsigned xb_ld(unsigned* p)              { return __hip_atomic_load(p, __ATOMIC_RELAXED, __HIP_MEMORY_SCOPE_AGENT); }
; __device__ __forceinline__ void xcd_barrier_complete(unsigned* bar, unsigned x, unsigned& nloc, unsigned& nx) {
;     const unsigned G = gridDim.x * gridDim.y * gridDim.z;
;     unsigned sum, cnt, mine, sp = 0u;
;     for (;;) {
;         sum = 0u; cnt = 0u; mine = 0u;
; #pragma unroll
;         for (unsigned j = 0; j < 16; ++j) { const unsigned c = xb_ld(&bar[XB_XCNT(j)]); sum += c; cnt += (c > 0u) ? 1u : 0u; mine = (j == x) ? c : mine; }
; __device__ __forceinline__ void xcd_barrier(const XcdBarrier& b) {
;     asm volatile("s_waitcnt vmcnt(0)" ::: "memory");
;     __syncthreads();
;     if (b.w0 == 0 && lane_id() == 0) {
;         unsigned* bar = b.bar;
;         __builtin_amdgcn_s_waitcnt(0);
;         unsigned nloc = b.st[0], nx = b.st[1];
;         if (nloc == 0u) { xcd_barrier_complete(bar, b.x, nloc, nx); b.st[0] = nloc; b.st[1] = nx; }
.Lscan_done:
.LBB0_675:
	s_or_b64 exec, exec, s[4:5]
	s_waitcnt vmcnt(0)
	s_barrier
	s_mov_b64 s[0:1], exec
	v_readlane_b32 s4, v255, 15
	v_readlane_b32 s5, v255, 16
	s_and_b64 s[4:5], s[0:1], s[4:5]
	s_mov_b64 exec, s[4:5]
	s_cbranch_execz .LBB0_727
	s_add_i32 s3, 0, 0x20200
	v_mov_b32_e32 v0, s3
	s_waitcnt vmcnt(0) expcnt(0) lgkmcnt(0)
	ds_read_b32 v2, v0
	s_add_i32 s3, 0, 0x20204
	v_mov_b32_e32 v0, s3
	ds_read_b32 v0, v0
	s_waitcnt lgkmcnt(1)
	v_cmp_ne_u32_e32 vcc, 0, v2
	s_cbranch_vccnz .LBB0_691
	v_readlane_b32 s4, v255, 8
	v_readlane_b32 s5, v255, 9
	s_load_dwordx2 s[8:9], s[4:5], 0x4
	s_add_u32 s4, s68, 0x80200
	s_addc_u32 s5, s69, 0
	s_add_u32 s6, s68, 0x80400
	s_addc_u32 s7, s69, 0
	s_waitcnt lgkmcnt(0)
	s_mul_i32 s3, s8, s96
	s_add_u32 s8, s68, 0x80500
	s_mul_i32 s3, s3, s9
	s_addc_u32 s9, s69, 0
	s_add_u32 s10, s68, 0x80600
	s_addc_u32 s11, s69, 0
	s_add_u32 s12, s68, 0x80700
	s_addc_u32 s13, s69, 0
	s_add_u32 s14, s68, 0x80800
	s_addc_u32 s15, s69, 0
	s_add_u32 s16, s68, 0x80900
	s_addc_u32 s17, s69, 0
	s_add_u32 s18, s68, 0x80a00
	s_addc_u32 s19, s69, 0
	s_add_u32 s20, s68, 0x80b00
	s_addc_u32 s21, s69, 0
	s_add_u32 s22, s68, 0x80c00
	s_addc_u32 s23, s69, 0
	s_add_u32 s24, s68, 0x80d00
	s_addc_u32 s25, s69, 0
	s_add_u32 s26, s68, 0x80e00
	s_addc_u32 s27, s69, 0
	s_add_u32 s28, s68, 0x80f00
	s_addc_u32 s29, s69, 0
	s_add_u32 s30, s68, 0x81000
	s_addc_u32 s31, s69, 0
	s_add_u32 s34, s68, 0x81100
	s_addc_u32 s35, s69, 0
	s_add_u32 s36, s68, 0x81200
	s_addc_u32 s37, s69, 0
	s_add_u32 s38, s68, 0x81300
	s_addc_u32 s39, s69, 0
	s_mov_b32 s46, 1
	v_mov_b32_e32 v16, 0
	s_branch .LBB0_679
